# final combine+LN phase: row-level load ladder (all row loads in flight at once; split-K column blocks rebuilt from their 7 partial tiles)
# speedup vs baseline: 1.0337x; 1.0133x over previous
; template <int SRC, int EXTRA, bool OUT8 = false> ...
;     ...
;             const int p0 = pos[2 * row], p1 = pos[2 * row + 1]; const float w0 = gwt[2 * row], w1 = gwt[2 * row + 1]; const float hm = hp.stats[2 * row], hr = hp.stats[2 * row + 1];
; #pragma unroll
;             for (int j = 0; j < 4; ++j) { const f32x4 a = (*(const f32x4*)(hp.src + (size_t)row * 1024 + 256 * j + 4 * lane) - hm) * hr * *(const f32x4*)(hp.g + 256 * j + 4 * lane) + *(const f32x4*)(hp.b + 256 * j + 4 * lane);
;                 f32x4 y[2];
; #pragma unroll
;                 for (int q = 0; q < 2; ++q) { const int p = q ? p1 : p0; const int t = __builtin_amdgcn_readfirstlane(tailid[(p >> 8) * 4 + j]);
;                     if (t < 0) y[q] = *(const f32x4*)(ys + (size_t)p * 1024 + 256 * j + 4 * lane);
;                     else { f32x4 acc = (f32x4){0.f, 0.f, 0.f, 0.f};
; #pragma unroll
;                         for (int sl = 0; sl < 7; ++sl) acc = acc + *(const f32x4*)(part + ((size_t)(t * 7 + sl) * 256 + (p & 255)) * 256 + 4 * lane);
;                         y[q] = acc; } }
.LBB0_2246:
	s_ashr_i32 s7, s6, 31
	s_lshl_b64 s[0:1], s[6:7], 2
	s_add_u32 s16, s26, s0
	s_addc_u32 s17, s27, s1
	global_load_dwordx2 v[44:45], v113, s[16:17]
	s_add_u32 s20, s28, s0
	s_addc_u32 s21, s29, s1
	s_add_u32 s0, s24, s0
	s_addc_u32 s1, s25, s1
	global_load_dwordx2 v[124:125], v113, s[0:1]
	global_load_dwordx2 v[122:123], v113, s[20:21]
	v_lshl_add_u64 v[160:161], s[8:9], 0, v[112:113]
	v_add_co_u32_e32 v160, vcc, s31, v160
	s_nop 1
	v_addc_co_u32_e32 v161, vcc, 0, v161, vcc
	global_load_dwordx4 v[40:43], v[160:161], off
	global_load_dwordx4 v[60:63], v[160:161], off offset:1024
	global_load_dwordx4 v[80:83], v[160:161], off offset:2048
	global_load_dwordx4 v[100:103], v[160:161], off offset:3072
	global_load_dwordx4 v[32:35], v[114:115], off
	global_load_dwordx4 v[52:55], v[114:115], off offset:1024
	global_load_dwordx4 v[72:75], v[114:115], off offset:2048
	global_load_dwordx4 v[88:91], v[114:115], off offset:3072
	global_load_dwordx4 v[36:39], v[116:117], off
	global_load_dwordx4 v[56:59], v[116:117], off offset:1024
	global_load_dwordx4 v[76:79], v[116:117], off offset:2048
	global_load_dwordx4 v[92:95], v[116:117], off offset:3072
	s_waitcnt vmcnt(14)
	v_readfirstlane_b32 s16, v44
	v_readfirstlane_b32 s22, v45
	s_ashr_i32 s0, s16, 6
	s_and_b32 s0, s0, -4
	s_ashr_i32 s1, s0, 31
	s_lshl_b64 s[0:1], s[0:1], 2
	s_add_u32 s18, s36, s0
	s_addc_u32 s19, s37, s1
	s_ashr_i32 s0, s22, 6
	s_and_b32 s0, s0, -4
	s_ashr_i32 s1, s0, 31
	s_lshl_b64 s[0:1], s[0:1], 2
	s_add_u32 s20, s36, s0
	s_addc_u32 s21, s37, s1
	global_load_dwordx4 v[168:171], v113, s[18:19]
	global_load_dwordx4 v[172:175], v113, s[20:21]
	s_ashr_i32 s17, s16, 31
	s_lshl_b64 s[0:1], s[16:17], 12
	v_lshl_add_u64 v[162:163], v[120:121], 0, s[0:1]
	s_ashr_i32 s23, s22, 31
	s_lshl_b64 s[0:1], s[22:23], 12
	v_lshl_add_u64 v[164:165], v[120:121], 0, s[0:1]
	global_load_dwordx4 v[44:47], v[162:163], off
	global_load_dwordx4 v[64:67], v[162:163], off offset:1024
	global_load_dwordx4 v[84:87], v[162:163], off offset:2048
	global_load_dwordx4 v[104:107], v[162:163], off offset:3072
	global_load_dwordx4 v[48:51], v[164:165], off
	global_load_dwordx4 v[68:71], v[164:165], off offset:1024
	global_load_dwordx4 v[96:99], v[164:165], off offset:2048
	global_load_dwordx4 v[108:111], v[164:165], off offset:3072
	s_waitcnt vmcnt(8)
	v_and_b32_e32 v176, v168, v169
	v_and_b32_e32 v177, v170, v171
	v_and_b32_e32 v178, v172, v173
	v_and_b32_e32 v179, v174, v175
	v_and_b32_e32 v176, v176, v177
	v_and_b32_e32 v178, v178, v179
	v_and_b32_e32 v176, v176, v178
	s_nop 0
	v_readfirstlane_b32 s0, v176
	s_waitcnt vmcnt(0)
	s_cmp_lt_i32 s0, 0
	s_cbranch_scc1 .LBB0_2278
	v_readfirstlane_b32 s1, v168
	s_cmp_lt_i32 s1, 0
	s_cbranch_scc1 .Lcomb_n00
	s_mul_i32 s20, s1, 7
	s_lshl_b32 s1, s16, 10
	s_and_b32 s2, s1, 0x3fc00
	s_mov_b32 s21, s3
	v_lshl_add_u64 v[176:177], v[118:119], 0, s[2:3]
	s_lshl_b64 s[38:39], s[20:21], 18
	v_lshl_add_u64 v[178:179], v[176:177], 0, s[38:39]
	global_load_dwordx4 v[128:131], v[178:179], off
	s_add_i32 s2, s20, 1
	s_lshl_b64 s[38:39], s[2:3], 18
	v_lshl_add_u64 v[182:183], v[176:177], 0, s[38:39]
	global_load_dwordx4 v[132:135], v[182:183], off
	s_add_i32 s2, s20, 2
	s_lshl_b64 s[38:39], s[2:3], 18
	v_lshl_add_u64 v[184:185], v[176:177], 0, s[38:39]
	global_load_dwordx4 v[136:139], v[184:185], off
	s_add_i32 s2, s20, 3
	s_lshl_b64 s[38:39], s[2:3], 18
	v_lshl_add_u64 v[186:187], v[176:177], 0, s[38:39]
	global_load_dwordx4 v[140:143], v[186:187], off
	s_add_i32 s2, s20, 4
	s_lshl_b64 s[38:39], s[2:3], 18
	v_lshl_add_u64 v[188:189], v[176:177], 0, s[38:39]
	global_load_dwordx4 v[144:147], v[188:189], off
	s_add_i32 s2, s20, 5
	s_lshl_b64 s[38:39], s[2:3], 18
	v_lshl_add_u64 v[190:191], v[176:177], 0, s[38:39]
	global_load_dwordx4 v[148:151], v[190:191], off
	s_add_i32 s2, s20, 6
	s_lshl_b64 s[38:39], s[2:3], 18
	v_lshl_add_u64 v[192:193], v[176:177], 0, s[38:39]
	global_load_dwordx4 v[152:155], v[192:193], off
	s_waitcnt vmcnt(6)
	v_pk_add_f32 v[46:47], v[130:131], 0 op_sel_hi:[1,0]
	v_pk_add_f32 v[44:45], v[128:129], 0 op_sel_hi:[1,0]
	s_waitcnt vmcnt(5)
	v_pk_add_f32 v[46:47], v[46:47], v[134:135]
	v_pk_add_f32 v[44:45], v[44:45], v[132:133]
	s_waitcnt vmcnt(4)
	v_pk_add_f32 v[46:47], v[46:47], v[138:139]
	v_pk_add_f32 v[44:45], v[44:45], v[136:137]
	s_waitcnt vmcnt(3)
	v_pk_add_f32 v[46:47], v[46:47], v[142:143]
	v_pk_add_f32 v[44:45], v[44:45], v[140:141]
	s_waitcnt vmcnt(2)
	v_pk_add_f32 v[46:47], v[46:47], v[146:147]
	v_pk_add_f32 v[44:45], v[44:45], v[144:145]
	s_waitcnt vmcnt(1)
	v_pk_add_f32 v[46:47], v[46:47], v[150:151]
	v_pk_add_f32 v[44:45], v[44:45], v[148:149]
	s_waitcnt vmcnt(0)
	v_pk_add_f32 v[46:47], v[46:47], v[154:155]
	v_pk_add_f32 v[44:45], v[44:45], v[152:153]
; template <int SRC, int EXTRA, bool OUT8 = false> ...
;     ...
;                 for (int q = 0; q < 2; ++q) { const int p = q ? p1 : p0; const int t = __builtin_amdgcn_readfirstlane(tailid[(p >> 8) * 4 + j]);
;                     if (t < 0) y[q] = *(const f32x4*)(ys + (size_t)p * 1024 + 256 * j + 4 * lane);
;                     else { f32x4 acc = (f32x4){0.f, 0.f, 0.f, 0.f};
; #pragma unroll
;                         for (int sl = 0; sl < 7; ++sl) acc = acc + *(const f32x4*)(part + ((size_t)(t * 7 + sl) * 256 + (p & 255)) * 256 + 4 * lane);
;                         y[q] = acc; } }
.Lcomb_n00:
	v_readfirstlane_b32 s1, v169
	s_cmp_lt_i32 s1, 0
	s_cbranch_scc1 .Lcomb_n01
	s_mul_i32 s20, s1, 7
	s_lshl_b32 s1, s16, 10
	s_and_b32 s2, s1, 0x3fc00
	s_mov_b32 s21, s3
	v_lshl_add_u64 v[176:177], v[118:119], 0, s[2:3]
	s_lshl_b64 s[38:39], s[20:21], 18
	v_lshl_add_u64 v[178:179], v[176:177], 0, s[38:39]
	global_load_dwordx4 v[128:131], v[178:179], off
	s_add_i32 s2, s20, 1
	s_lshl_b64 s[38:39], s[2:3], 18
	v_lshl_add_u64 v[182:183], v[176:177], 0, s[38:39]
	global_load_dwordx4 v[132:135], v[182:183], off
	s_add_i32 s2, s20, 2
	s_lshl_b64 s[38:39], s[2:3], 18
	v_lshl_add_u64 v[184:185], v[176:177], 0, s[38:39]
	global_load_dwordx4 v[136:139], v[184:185], off
	s_add_i32 s2, s20, 3
	s_lshl_b64 s[38:39], s[2:3], 18
	v_lshl_add_u64 v[186:187], v[176:177], 0, s[38:39]
	global_load_dwordx4 v[140:143], v[186:187], off
	s_add_i32 s2, s20, 4
	s_lshl_b64 s[38:39], s[2:3], 18
	v_lshl_add_u64 v[188:189], v[176:177], 0, s[38:39]
	global_load_dwordx4 v[144:147], v[188:189], off
	s_add_i32 s2, s20, 5
	s_lshl_b64 s[38:39], s[2:3], 18
	v_lshl_add_u64 v[190:191], v[176:177], 0, s[38:39]
	global_load_dwordx4 v[148:151], v[190:191], off
	s_add_i32 s2, s20, 6
	s_lshl_b64 s[38:39], s[2:3], 18
	v_lshl_add_u64 v[192:193], v[176:177], 0, s[38:39]
	global_load_dwordx4 v[152:155], v[192:193], off
	s_waitcnt vmcnt(6)
	v_pk_add_f32 v[66:67], v[130:131], 0 op_sel_hi:[1,0]
	v_pk_add_f32 v[64:65], v[128:129], 0 op_sel_hi:[1,0]
	s_waitcnt vmcnt(5)
	v_pk_add_f32 v[66:67], v[66:67], v[134:135]
	v_pk_add_f32 v[64:65], v[64:65], v[132:133]
	s_waitcnt vmcnt(4)
	v_pk_add_f32 v[66:67], v[66:67], v[138:139]
	v_pk_add_f32 v[64:65], v[64:65], v[136:137]
	s_waitcnt vmcnt(3)
	v_pk_add_f32 v[66:67], v[66:67], v[142:143]
	v_pk_add_f32 v[64:65], v[64:65], v[140:141]
	s_waitcnt vmcnt(2)
	v_pk_add_f32 v[66:67], v[66:67], v[146:147]
	v_pk_add_f32 v[64:65], v[64:65], v[144:145]
	s_waitcnt vmcnt(1)
	v_pk_add_f32 v[66:67], v[66:67], v[150:151]
	v_pk_add_f32 v[64:65], v[64:65], v[148:149]
	s_waitcnt vmcnt(0)
	v_pk_add_f32 v[66:67], v[66:67], v[154:155]
	v_pk_add_f32 v[64:65], v[64:65], v[152:153]
.Lcomb_n01:
	v_readfirstlane_b32 s1, v170
	s_cmp_lt_i32 s1, 0
	s_cbranch_scc1 .Lcomb_n02
	s_mul_i32 s20, s1, 7
	s_lshl_b32 s1, s16, 10
	s_and_b32 s2, s1, 0x3fc00
	s_mov_b32 s21, s3
	v_lshl_add_u64 v[176:177], v[118:119], 0, s[2:3]
	s_lshl_b64 s[38:39], s[20:21], 18
	v_lshl_add_u64 v[178:179], v[176:177], 0, s[38:39]
	global_load_dwordx4 v[128:131], v[178:179], off
	s_add_i32 s2, s20, 1
	s_lshl_b64 s[38:39], s[2:3], 18
	v_lshl_add_u64 v[182:183], v[176:177], 0, s[38:39]
	global_load_dwordx4 v[132:135], v[182:183], off
	s_add_i32 s2, s20, 2
	s_lshl_b64 s[38:39], s[2:3], 18
	v_lshl_add_u64 v[184:185], v[176:177], 0, s[38:39]
	global_load_dwordx4 v[136:139], v[184:185], off
	s_add_i32 s2, s20, 3
	s_lshl_b64 s[38:39], s[2:3], 18
	v_lshl_add_u64 v[186:187], v[176:177], 0, s[38:39]
	global_load_dwordx4 v[140:143], v[186:187], off
	s_add_i32 s2, s20, 4
	s_lshl_b64 s[38:39], s[2:3], 18
	v_lshl_add_u64 v[188:189], v[176:177], 0, s[38:39]
	global_load_dwordx4 v[144:147], v[188:189], off
	s_add_i32 s2, s20, 5
	s_lshl_b64 s[38:39], s[2:3], 18
	v_lshl_add_u64 v[190:191], v[176:177], 0, s[38:39]
	global_load_dwordx4 v[148:151], v[190:191], off
	s_add_i32 s2, s20, 6
	s_lshl_b64 s[38:39], s[2:3], 18
	v_lshl_add_u64 v[192:193], v[176:177], 0, s[38:39]
	global_load_dwordx4 v[152:155], v[192:193], off
	s_waitcnt vmcnt(6)
	v_pk_add_f32 v[86:87], v[130:131], 0 op_sel_hi:[1,0]
	v_pk_add_f32 v[84:85], v[128:129], 0 op_sel_hi:[1,0]
	s_waitcnt vmcnt(5)
	v_pk_add_f32 v[86:87], v[86:87], v[134:135]
	v_pk_add_f32 v[84:85], v[84:85], v[132:133]
	s_waitcnt vmcnt(4)
	v_pk_add_f32 v[86:87], v[86:87], v[138:139]
	v_pk_add_f32 v[84:85], v[84:85], v[136:137]
	s_waitcnt vmcnt(3)
	v_pk_add_f32 v[86:87], v[86:87], v[142:143]
	v_pk_add_f32 v[84:85], v[84:85], v[140:141]
	s_waitcnt vmcnt(2)
	v_pk_add_f32 v[86:87], v[86:87], v[146:147]
	v_pk_add_f32 v[84:85], v[84:85], v[144:145]
	s_waitcnt vmcnt(1)
	v_pk_add_f32 v[86:87], v[86:87], v[150:151]
	v_pk_add_f32 v[84:85], v[84:85], v[148:149]
	s_waitcnt vmcnt(0)
	v_pk_add_f32 v[86:87], v[86:87], v[154:155]
	v_pk_add_f32 v[84:85], v[84:85], v[152:153]
.Lcomb_n02:
	v_readfirstlane_b32 s1, v171
	s_cmp_lt_i32 s1, 0
	s_cbranch_scc1 .Lcomb_n03
	s_mul_i32 s20, s1, 7
	s_lshl_b32 s1, s16, 10
	s_and_b32 s2, s1, 0x3fc00
	s_mov_b32 s21, s3
	v_lshl_add_u64 v[176:177], v[118:119], 0, s[2:3]
	s_lshl_b64 s[38:39], s[20:21], 18
	v_lshl_add_u64 v[178:179], v[176:177], 0, s[38:39]
	global_load_dwordx4 v[128:131], v[178:179], off
	s_add_i32 s2, s20, 1
	s_lshl_b64 s[38:39], s[2:3], 18
	v_lshl_add_u64 v[182:183], v[176:177], 0, s[38:39]
	global_load_dwordx4 v[132:135], v[182:183], off
	s_add_i32 s2, s20, 2
	s_lshl_b64 s[38:39], s[2:3], 18
	v_lshl_add_u64 v[184:185], v[176:177], 0, s[38:39]
	global_load_dwordx4 v[136:139], v[184:185], off
	s_add_i32 s2, s20, 3
	s_lshl_b64 s[38:39], s[2:3], 18
	v_lshl_add_u64 v[186:187], v[176:177], 0, s[38:39]
	global_load_dwordx4 v[140:143], v[186:187], off
	s_add_i32 s2, s20, 4
	s_lshl_b64 s[38:39], s[2:3], 18
	v_lshl_add_u64 v[188:189], v[176:177], 0, s[38:39]
	global_load_dwordx4 v[144:147], v[188:189], off
	s_add_i32 s2, s20, 5
	s_lshl_b64 s[38:39], s[2:3], 18
	v_lshl_add_u64 v[190:191], v[176:177], 0, s[38:39]
	global_load_dwordx4 v[148:151], v[190:191], off
	s_add_i32 s2, s20, 6
	s_lshl_b64 s[38:39], s[2:3], 18
	v_lshl_add_u64 v[192:193], v[176:177], 0, s[38:39]
	global_load_dwordx4 v[152:155], v[192:193], off
	s_waitcnt vmcnt(6)
	v_pk_add_f32 v[106:107], v[130:131], 0 op_sel_hi:[1,0]
	v_pk_add_f32 v[104:105], v[128:129], 0 op_sel_hi:[1,0]
	s_waitcnt vmcnt(5)
	v_pk_add_f32 v[106:107], v[106:107], v[134:135]
	v_pk_add_f32 v[104:105], v[104:105], v[132:133]
	s_waitcnt vmcnt(4)
	v_pk_add_f32 v[106:107], v[106:107], v[138:139]
	v_pk_add_f32 v[104:105], v[104:105], v[136:137]
	s_waitcnt vmcnt(3)
	v_pk_add_f32 v[106:107], v[106:107], v[142:143]
	v_pk_add_f32 v[104:105], v[104:105], v[140:141]
	s_waitcnt vmcnt(2)
	v_pk_add_f32 v[106:107], v[106:107], v[146:147]
	v_pk_add_f32 v[104:105], v[104:105], v[144:145]
	s_waitcnt vmcnt(1)
	v_pk_add_f32 v[106:107], v[106:107], v[150:151]
	v_pk_add_f32 v[104:105], v[104:105], v[148:149]
	s_waitcnt vmcnt(0)
	v_pk_add_f32 v[106:107], v[106:107], v[154:155]
	v_pk_add_f32 v[104:105], v[104:105], v[152:153]
; template <int SRC, int EXTRA, bool OUT8 = false> ...
;     ...
;                 for (int q = 0; q < 2; ++q) { const int p = q ? p1 : p0; const int t = __builtin_amdgcn_readfirstlane(tailid[(p >> 8) * 4 + j]);
;                     if (t < 0) y[q] = *(const f32x4*)(ys + (size_t)p * 1024 + 256 * j + 4 * lane);
;                     else { f32x4 acc = (f32x4){0.f, 0.f, 0.f, 0.f};
; #pragma unroll
;                         for (int sl = 0; sl < 7; ++sl) acc = acc + *(const f32x4*)(part + ((size_t)(t * 7 + sl) * 256 + (p & 255)) * 256 + 4 * lane);
;                         y[q] = acc; } }
.Lcomb_n03:
	v_readfirstlane_b32 s1, v172
	s_cmp_lt_i32 s1, 0
	s_cbranch_scc1 .Lcomb_n10
	s_mul_i32 s20, s1, 7
	s_lshl_b32 s1, s22, 10
	s_and_b32 s2, s1, 0x3fc00
	s_mov_b32 s21, s3
	v_lshl_add_u64 v[176:177], v[118:119], 0, s[2:3]
	s_lshl_b64 s[38:39], s[20:21], 18
	v_lshl_add_u64 v[178:179], v[176:177], 0, s[38:39]
	global_load_dwordx4 v[128:131], v[178:179], off
	s_add_i32 s2, s20, 1
	s_lshl_b64 s[38:39], s[2:3], 18
	v_lshl_add_u64 v[182:183], v[176:177], 0, s[38:39]
	global_load_dwordx4 v[132:135], v[182:183], off
	s_add_i32 s2, s20, 2
	s_lshl_b64 s[38:39], s[2:3], 18
	v_lshl_add_u64 v[184:185], v[176:177], 0, s[38:39]
	global_load_dwordx4 v[136:139], v[184:185], off
	s_add_i32 s2, s20, 3
	s_lshl_b64 s[38:39], s[2:3], 18
	v_lshl_add_u64 v[186:187], v[176:177], 0, s[38:39]
	global_load_dwordx4 v[140:143], v[186:187], off
	s_add_i32 s2, s20, 4
	s_lshl_b64 s[38:39], s[2:3], 18
	v_lshl_add_u64 v[188:189], v[176:177], 0, s[38:39]
	global_load_dwordx4 v[144:147], v[188:189], off
	s_add_i32 s2, s20, 5
	s_lshl_b64 s[38:39], s[2:3], 18
	v_lshl_add_u64 v[190:191], v[176:177], 0, s[38:39]
	global_load_dwordx4 v[148:151], v[190:191], off
	s_add_i32 s2, s20, 6
	s_lshl_b64 s[38:39], s[2:3], 18
	v_lshl_add_u64 v[192:193], v[176:177], 0, s[38:39]
	global_load_dwordx4 v[152:155], v[192:193], off
	s_waitcnt vmcnt(6)
	v_pk_add_f32 v[50:51], v[130:131], 0 op_sel_hi:[1,0]
	v_pk_add_f32 v[48:49], v[128:129], 0 op_sel_hi:[1,0]
	s_waitcnt vmcnt(5)
	v_pk_add_f32 v[50:51], v[50:51], v[134:135]
	v_pk_add_f32 v[48:49], v[48:49], v[132:133]
	s_waitcnt vmcnt(4)
	v_pk_add_f32 v[50:51], v[50:51], v[138:139]
	v_pk_add_f32 v[48:49], v[48:49], v[136:137]
	s_waitcnt vmcnt(3)
	v_pk_add_f32 v[50:51], v[50:51], v[142:143]
	v_pk_add_f32 v[48:49], v[48:49], v[140:141]
	s_waitcnt vmcnt(2)
	v_pk_add_f32 v[50:51], v[50:51], v[146:147]
	v_pk_add_f32 v[48:49], v[48:49], v[144:145]
	s_waitcnt vmcnt(1)
	v_pk_add_f32 v[50:51], v[50:51], v[150:151]
	v_pk_add_f32 v[48:49], v[48:49], v[148:149]
	s_waitcnt vmcnt(0)
	v_pk_add_f32 v[50:51], v[50:51], v[154:155]
	v_pk_add_f32 v[48:49], v[48:49], v[152:153]
.Lcomb_n10:
	v_readfirstlane_b32 s1, v173
	s_cmp_lt_i32 s1, 0
	s_cbranch_scc1 .Lcomb_n11
	s_mul_i32 s20, s1, 7
	s_lshl_b32 s1, s22, 10
	s_and_b32 s2, s1, 0x3fc00
	s_mov_b32 s21, s3
	v_lshl_add_u64 v[176:177], v[118:119], 0, s[2:3]
	s_lshl_b64 s[38:39], s[20:21], 18
	v_lshl_add_u64 v[178:179], v[176:177], 0, s[38:39]
	global_load_dwordx4 v[128:131], v[178:179], off
	s_add_i32 s2, s20, 1
	s_lshl_b64 s[38:39], s[2:3], 18
	v_lshl_add_u64 v[182:183], v[176:177], 0, s[38:39]
	global_load_dwordx4 v[132:135], v[182:183], off
	s_add_i32 s2, s20, 2
	s_lshl_b64 s[38:39], s[2:3], 18
	v_lshl_add_u64 v[184:185], v[176:177], 0, s[38:39]
	global_load_dwordx4 v[136:139], v[184:185], off
	s_add_i32 s2, s20, 3
	s_lshl_b64 s[38:39], s[2:3], 18
	v_lshl_add_u64 v[186:187], v[176:177], 0, s[38:39]
	global_load_dwordx4 v[140:143], v[186:187], off
	s_add_i32 s2, s20, 4
	s_lshl_b64 s[38:39], s[2:3], 18
	v_lshl_add_u64 v[188:189], v[176:177], 0, s[38:39]
	global_load_dwordx4 v[144:147], v[188:189], off
	s_add_i32 s2, s20, 5
	s_lshl_b64 s[38:39], s[2:3], 18
	v_lshl_add_u64 v[190:191], v[176:177], 0, s[38:39]
	global_load_dwordx4 v[148:151], v[190:191], off
	s_add_i32 s2, s20, 6
	s_lshl_b64 s[38:39], s[2:3], 18
	v_lshl_add_u64 v[192:193], v[176:177], 0, s[38:39]
	global_load_dwordx4 v[152:155], v[192:193], off
	s_waitcnt vmcnt(6)
	v_pk_add_f32 v[70:71], v[130:131], 0 op_sel_hi:[1,0]
	v_pk_add_f32 v[68:69], v[128:129], 0 op_sel_hi:[1,0]
	s_waitcnt vmcnt(5)
	v_pk_add_f32 v[70:71], v[70:71], v[134:135]
	v_pk_add_f32 v[68:69], v[68:69], v[132:133]
	s_waitcnt vmcnt(4)
	v_pk_add_f32 v[70:71], v[70:71], v[138:139]
	v_pk_add_f32 v[68:69], v[68:69], v[136:137]
	s_waitcnt vmcnt(3)
	v_pk_add_f32 v[70:71], v[70:71], v[142:143]
	v_pk_add_f32 v[68:69], v[68:69], v[140:141]
	s_waitcnt vmcnt(2)
	v_pk_add_f32 v[70:71], v[70:71], v[146:147]
	v_pk_add_f32 v[68:69], v[68:69], v[144:145]
	s_waitcnt vmcnt(1)
	v_pk_add_f32 v[70:71], v[70:71], v[150:151]
	v_pk_add_f32 v[68:69], v[68:69], v[148:149]
	s_waitcnt vmcnt(0)
	v_pk_add_f32 v[70:71], v[70:71], v[154:155]
	v_pk_add_f32 v[68:69], v[68:69], v[152:153]
.Lcomb_n11:
	v_readfirstlane_b32 s1, v174
	s_cmp_lt_i32 s1, 0
	s_cbranch_scc1 .Lcomb_n12
	s_mul_i32 s20, s1, 7
	s_lshl_b32 s1, s22, 10
	s_and_b32 s2, s1, 0x3fc00
	s_mov_b32 s21, s3
	v_lshl_add_u64 v[176:177], v[118:119], 0, s[2:3]
	s_lshl_b64 s[38:39], s[20:21], 18
	v_lshl_add_u64 v[178:179], v[176:177], 0, s[38:39]
	global_load_dwordx4 v[128:131], v[178:179], off
	s_add_i32 s2, s20, 1
	s_lshl_b64 s[38:39], s[2:3], 18
	v_lshl_add_u64 v[182:183], v[176:177], 0, s[38:39]
	global_load_dwordx4 v[132:135], v[182:183], off
	s_add_i32 s2, s20, 2
	s_lshl_b64 s[38:39], s[2:3], 18
	v_lshl_add_u64 v[184:185], v[176:177], 0, s[38:39]
	global_load_dwordx4 v[136:139], v[184:185], off
	s_add_i32 s2, s20, 3
	s_lshl_b64 s[38:39], s[2:3], 18
	v_lshl_add_u64 v[186:187], v[176:177], 0, s[38:39]
	global_load_dwordx4 v[140:143], v[186:187], off
	s_add_i32 s2, s20, 4
	s_lshl_b64 s[38:39], s[2:3], 18
	v_lshl_add_u64 v[188:189], v[176:177], 0, s[38:39]
	global_load_dwordx4 v[144:147], v[188:189], off
	s_add_i32 s2, s20, 5
	s_lshl_b64 s[38:39], s[2:3], 18
	v_lshl_add_u64 v[190:191], v[176:177], 0, s[38:39]
	global_load_dwordx4 v[148:151], v[190:191], off
	s_add_i32 s2, s20, 6
	s_lshl_b64 s[38:39], s[2:3], 18
	v_lshl_add_u64 v[192:193], v[176:177], 0, s[38:39]
	global_load_dwordx4 v[152:155], v[192:193], off
	s_waitcnt vmcnt(6)
	v_pk_add_f32 v[98:99], v[130:131], 0 op_sel_hi:[1,0]
	v_pk_add_f32 v[96:97], v[128:129], 0 op_sel_hi:[1,0]
	s_waitcnt vmcnt(5)
	v_pk_add_f32 v[98:99], v[98:99], v[134:135]
	v_pk_add_f32 v[96:97], v[96:97], v[132:133]
	s_waitcnt vmcnt(4)
	v_pk_add_f32 v[98:99], v[98:99], v[138:139]
	v_pk_add_f32 v[96:97], v[96:97], v[136:137]
	s_waitcnt vmcnt(3)
	v_pk_add_f32 v[98:99], v[98:99], v[142:143]
	v_pk_add_f32 v[96:97], v[96:97], v[140:141]
	s_waitcnt vmcnt(2)
	v_pk_add_f32 v[98:99], v[98:99], v[146:147]
	v_pk_add_f32 v[96:97], v[96:97], v[144:145]
	s_waitcnt vmcnt(1)
	v_pk_add_f32 v[98:99], v[98:99], v[150:151]
	v_pk_add_f32 v[96:97], v[96:97], v[148:149]
	s_waitcnt vmcnt(0)
	v_pk_add_f32 v[98:99], v[98:99], v[154:155]
	v_pk_add_f32 v[96:97], v[96:97], v[152:153]
; template <int SRC, int EXTRA, bool OUT8 = false> ...
;     ...
;                 for (int q = 0; q < 2; ++q) { const int p = q ? p1 : p0; const int t = __builtin_amdgcn_readfirstlane(tailid[(p >> 8) * 4 + j]);
;                     if (t < 0) y[q] = *(const f32x4*)(ys + (size_t)p * 1024 + 256 * j + 4 * lane);
;                     else { f32x4 acc = (f32x4){0.f, 0.f, 0.f, 0.f};
; #pragma unroll
;                         for (int sl = 0; sl < 7; ++sl) acc = acc + *(const f32x4*)(part + ((size_t)(t * 7 + sl) * 256 + (p & 255)) * 256 + 4 * lane);
;                         y[q] = acc; } }
;                 v[j] = a * ALPHA + y[0] * w0 + y[1] * w1; }
.Lcomb_n12:
	v_readfirstlane_b32 s1, v175
	s_cmp_lt_i32 s1, 0
	s_cbranch_scc1 .Lcomb_n13
	s_mul_i32 s20, s1, 7
	s_lshl_b32 s1, s22, 10
	s_and_b32 s2, s1, 0x3fc00
	s_mov_b32 s21, s3
	v_lshl_add_u64 v[176:177], v[118:119], 0, s[2:3]
	s_lshl_b64 s[38:39], s[20:21], 18
	v_lshl_add_u64 v[178:179], v[176:177], 0, s[38:39]
	global_load_dwordx4 v[128:131], v[178:179], off
	s_add_i32 s2, s20, 1
	s_lshl_b64 s[38:39], s[2:3], 18
	v_lshl_add_u64 v[182:183], v[176:177], 0, s[38:39]
	global_load_dwordx4 v[132:135], v[182:183], off
	s_add_i32 s2, s20, 2
	s_lshl_b64 s[38:39], s[2:3], 18
	v_lshl_add_u64 v[184:185], v[176:177], 0, s[38:39]
	global_load_dwordx4 v[136:139], v[184:185], off
	s_add_i32 s2, s20, 3
	s_lshl_b64 s[38:39], s[2:3], 18
	v_lshl_add_u64 v[186:187], v[176:177], 0, s[38:39]
	global_load_dwordx4 v[140:143], v[186:187], off
	s_add_i32 s2, s20, 4
	s_lshl_b64 s[38:39], s[2:3], 18
	v_lshl_add_u64 v[188:189], v[176:177], 0, s[38:39]
	global_load_dwordx4 v[144:147], v[188:189], off
	s_add_i32 s2, s20, 5
	s_lshl_b64 s[38:39], s[2:3], 18
	v_lshl_add_u64 v[190:191], v[176:177], 0, s[38:39]
	global_load_dwordx4 v[148:151], v[190:191], off
	s_add_i32 s2, s20, 6
	s_lshl_b64 s[38:39], s[2:3], 18
	v_lshl_add_u64 v[192:193], v[176:177], 0, s[38:39]
	global_load_dwordx4 v[152:155], v[192:193], off
	s_waitcnt vmcnt(6)
	v_pk_add_f32 v[110:111], v[130:131], 0 op_sel_hi:[1,0]
	v_pk_add_f32 v[108:109], v[128:129], 0 op_sel_hi:[1,0]
	s_waitcnt vmcnt(5)
	v_pk_add_f32 v[110:111], v[110:111], v[134:135]
	v_pk_add_f32 v[108:109], v[108:109], v[132:133]
	s_waitcnt vmcnt(4)
	v_pk_add_f32 v[110:111], v[110:111], v[138:139]
	v_pk_add_f32 v[108:109], v[108:109], v[136:137]
	s_waitcnt vmcnt(3)
	v_pk_add_f32 v[110:111], v[110:111], v[142:143]
	v_pk_add_f32 v[108:109], v[108:109], v[140:141]
	s_waitcnt vmcnt(2)
	v_pk_add_f32 v[110:111], v[110:111], v[146:147]
	v_pk_add_f32 v[108:109], v[108:109], v[144:145]
	s_waitcnt vmcnt(1)
	v_pk_add_f32 v[110:111], v[110:111], v[150:151]
	v_pk_add_f32 v[108:109], v[108:109], v[148:149]
	s_waitcnt vmcnt(0)
	v_pk_add_f32 v[110:111], v[110:111], v[154:155]
	v_pk_add_f32 v[108:109], v[108:109], v[152:153]
.Lcomb_n13:
.LBB0_2278:
	v_sub_f32_e32 v83, v83, v124
	v_sub_f32_e32 v82, v82, v124
	v_sub_f32_e32 v81, v81, v124
	v_sub_f32_e32 v80, v80, v124
	v_pk_mul_f32 v[80:81], v[124:125], v[80:81] op_sel:[1,0]
	v_pk_mul_f32 v[82:83], v[124:125], v[82:83] op_sel:[1,0]
	v_sub_f32_e32 v43, v43, v124
	v_sub_f32_e32 v42, v42, v124
	v_sub_f32_e32 v41, v41, v124
	v_sub_f32_e32 v40, v40, v124
	v_pk_fma_f32 v[74:75], v[74:75], v[82:83], v[78:79]
	v_pk_fma_f32 v[72:73], v[72:73], v[80:81], v[76:77]
	v_pk_mul_f32 v[78:79], v[122:123], v[84:85] op_sel_hi:[0,1]
	v_pk_mul_f32 v[40:41], v[124:125], v[40:41] op_sel:[1,0]
	v_pk_mul_f32 v[42:43], v[124:125], v[42:43] op_sel:[1,0]
	v_pk_mul_f32 v[76:77], v[122:123], v[86:87] op_sel_hi:[0,1]
	v_pk_fma_f32 v[78:79], v[72:73], s[14:15], v[78:79] op_sel_hi:[1,0,1]
	v_pk_fma_f32 v[34:35], v[34:35], v[42:43], v[38:39]
	v_pk_fma_f32 v[32:33], v[32:33], v[40:41], v[36:37]
	v_pk_mul_f32 v[38:39], v[122:123], v[44:45] op_sel_hi:[0,1]
	v_pk_fma_f32 v[72:73], v[74:75], s[14:15], v[76:77] op_sel_hi:[1,0,1]
	v_pk_fma_f32 v[74:75], v[122:123], v[96:97], v[78:79] op_sel:[1,0,0]
	v_sub_f32_e32 v79, v101, v124
	v_sub_f32_e32 v78, v100, v124
	v_sub_f32_e32 v63, v63, v124
	v_sub_f32_e32 v62, v62, v124
	v_sub_f32_e32 v61, v61, v124
	v_sub_f32_e32 v60, v60, v124
	v_pk_mul_f32 v[36:37], v[122:123], v[46:47] op_sel_hi:[0,1]
	v_pk_fma_f32 v[32:33], v[32:33], s[14:15], v[38:39] op_sel_hi:[1,0,1]
	v_sub_f32_e32 v77, v103, v124
	v_sub_f32_e32 v76, v102, v124
	v_pk_mul_f32 v[60:61], v[124:125], v[60:61] op_sel:[1,0]
	v_pk_mul_f32 v[62:63], v[124:125], v[62:63] op_sel:[1,0]
	v_pk_fma_f32 v[34:35], v[34:35], s[14:15], v[36:37] op_sel_hi:[1,0,1]
	v_pk_fma_f32 v[38:39], v[122:123], v[48:49], v[32:33] op_sel:[1,0,0]
	v_pk_mul_f32 v[32:33], v[124:125], v[78:79] op_sel:[1,0]
	v_pk_fma_f32 v[54:55], v[54:55], v[62:63], v[58:59]
	v_pk_fma_f32 v[52:53], v[52:53], v[60:61], v[56:57]
	v_pk_mul_f32 v[56:57], v[122:123], v[66:67] op_sel_hi:[0,1]
	v_pk_mul_f32 v[58:59], v[122:123], v[64:65] op_sel_hi:[0,1]
	v_pk_fma_f32 v[36:37], v[122:123], v[50:51], v[34:35] op_sel:[1,0,0]
	v_pk_mul_f32 v[34:35], v[124:125], v[76:77] op_sel:[1,0]
	v_pk_fma_f32 v[32:33], v[88:89], v[32:33], v[92:93]
	v_pk_mul_f32 v[42:43], v[122:123], v[104:105] op_sel_hi:[0,1]
	v_pk_fma_f32 v[58:59], v[52:53], s[14:15], v[58:59] op_sel_hi:[1,0,1]
	v_pk_fma_f32 v[52:53], v[54:55], s[14:15], v[56:57] op_sel_hi:[1,0,1]
	v_pk_fma_f32 v[34:35], v[90:91], v[34:35], v[94:95]
	v_pk_mul_f32 v[40:41], v[122:123], v[106:107] op_sel_hi:[0,1]
	v_pk_fma_f32 v[42:43], v[32:33], s[14:15], v[42:43] op_sel_hi:[1,0,1]
	v_pk_fma_f32 v[52:53], v[122:123], v[70:71], v[52:53] op_sel:[1,0,0]
	v_pk_fma_f32 v[54:55], v[122:123], v[68:69], v[58:59] op_sel:[1,0,0]
	v_pk_fma_f32 v[32:33], v[34:35], s[14:15], v[40:41] op_sel_hi:[1,0,1]
	s_waitcnt vmcnt(0)
; template <int SRC, int EXTRA, bool OUT8 = false> ...
;     ...
;         float s = 0.f;
; #pragma unroll
;         for (int j = 0; j < 4; ++j) s += (v[j].x + v[j].y) + (v[j].z + v[j].w);
;         const float mean = wave_sum(s) * (1.f / 1024.f); float s2 = 0.f;
; #pragma unroll
;         for (int j = 0; j < 4; ++j) { v[j] = v[j] - mean; s2 += (v[j].x * v[j].x + v[j].y * v[j].y) + (v[j].z * v[j].z + v[j].w * v[j].w); }
;         const float rstd = 1.f / sqrtf(wave_sum(s2) * (1.f / 1024.f) + LN_EPS);
;         if (stats && lane == 0) { stats[2 * row] = mean; stats[2 * row + 1] = rstd; }
; #pragma unroll
;         for (int j = 0; j < 4; ++j) { v[j] = v[j] * rstd * gv[j] + bv[j]; if (of32) *(f32x4*)(of32 + (size_t)row * 1024 + 256 * j + 4 * lane) = v[j];
	v_pk_fma_f32 v[34:35], v[122:123], v[108:109], v[42:43] op_sel:[1,0,0]
	v_pk_mov_b32 v[40:41], v[38:39], v[36:37] op_sel:[1,0]
	v_mov_b32_e32 v42, v38
	v_mov_b32_e32 v43, v37
	v_pk_add_f32 v[40:41], v[40:41], v[42:43]
	v_pk_mov_b32 v[42:43], v[54:55], v[52:53] op_sel:[1,0]
	v_mov_b32_e32 v44, v54
	v_mov_b32_e32 v45, v53
	v_pk_add_f32 v[42:43], v[42:43], v[44:45]
	v_pk_fma_f32 v[72:73], v[122:123], v[98:99], v[72:73] op_sel:[1,0,0]
	v_pk_fma_f32 v[32:33], v[122:123], v[110:111], v[32:33] op_sel:[1,0,0]
	v_add_f32_e32 v40, v40, v41
	v_pk_add_f32 v[42:43], v[42:43], v[42:43] op_sel:[0,1] op_sel_hi:[1,0]
	v_add_f32_e32 v40, 0, v40
	v_add_f32_e32 v44, v74, v75
	v_add_f32_e32 v46, v72, v73
	v_mov_b32_e32 v41, v34
	v_mov_b32_e32 v43, v35
	v_mov_b32_e32 v45, v32
	v_mov_b32_e32 v47, v33
	v_pk_add_f32 v[40:41], v[40:41], v[42:43]
	v_pk_add_f32 v[42:43], v[44:45], v[46:47]
	s_andn2_b64 vcc, exec, s[4:5]
	v_pk_add_f32 v[40:41], v[40:41], v[42:43]
	s_nop 0
	v_add_f32_e32 v40, v40, v41
	s_nop 0
	s_nop 1
	v_mov_b32_dpp v41, v40 quad_perm:[1,0,3,2] row_mask:0xf bank_mask:0xf
	v_add_f32_e32 v40, v40, v41
	s_nop 0
	s_nop 1
	v_mov_b32_dpp v41, v40 quad_perm:[2,3,0,1] row_mask:0xf bank_mask:0xf
	v_add_f32_e32 v40, v40, v41
	s_nop 0
	s_nop 1
	v_mov_b32_dpp v41, v40 row_shl:4 row_mask:0xf bank_mask:0x5
	v_mov_b32_dpp v41, v40 row_shr:4 row_mask:0xf bank_mask:0xa
	v_add_f32_e32 v40, v40, v41
	s_nop 0
	s_nop 1
	v_mov_b32_dpp v41, v40 row_ror:8 row_mask:0xf bank_mask:0xf
	v_add_f32_e32 v40, v40, v41
	s_nop 0
	v_mov_b32_e32 v41, v40
	v_mov_b32_e32 v200, v40
	s_nop 1
	v_permlane16_swap_b32_e32 v41, v200
	v_cndmask_b32_e64 v41, v200, v41, s[98:99]
	v_add_f32_e32 v40, v40, v41
	s_nop 0
	v_mov_b32_e32 v41, v40
	v_mov_b32_e32 v200, v40
	s_nop 1
	v_permlane32_swap_b32_e32 v41, v200
	v_cndmask_b32_e64 v41, v200, v41, s[100:101]
	v_add_f32_e32 v40, v40, v41
	v_fmamk_f32 v37, v40, 0xba800000, v37
	v_fmamk_f32 v39, v40, 0xba800000, v39
	v_fmac_f32_e32 v36, 0xba800000, v40
	v_fmac_f32_e32 v38, 0xba800000, v40
	v_mul_f32_e32 v41, v39, v39
	v_mul_f32_e32 v42, v37, v37
	v_fmac_f32_e32 v41, v38, v38
	v_fmac_f32_e32 v42, v36, v36
	v_fmamk_f32 v53, v40, 0xba800000, v53
	v_fmamk_f32 v55, v40, 0xba800000, v55
	v_add_f32_e32 v41, v41, v42
	v_fmac_f32_e32 v52, 0xba800000, v40
	v_fmac_f32_e32 v54, 0xba800000, v40
	v_mul_f32_e32 v42, v55, v55
	v_mul_f32_e32 v43, v53, v53
	v_fmac_f32_e32 v42, v54, v54
	v_fmac_f32_e32 v43, v52, v52
	v_add_f32_e32 v42, v42, v43
	v_fmamk_f32 v73, v40, 0xba800000, v73
	v_fmamk_f32 v75, v40, 0xba800000, v75
	v_add_f32_e32 v41, v41, v42
	v_fmac_f32_e32 v72, 0xba800000, v40
	v_fmac_f32_e32 v74, 0xba800000, v40
	v_mul_f32_e32 v42, v75, v75
	v_mul_f32_e32 v43, v73, v73
	v_fmac_f32_e32 v42, v74, v74
	v_fmac_f32_e32 v43, v72, v72
	v_add_f32_e32 v42, v42, v43
	v_fmamk_f32 v33, v40, 0xba800000, v33
	v_fmamk_f32 v35, v40, 0xba800000, v35
	v_add_f32_e32 v41, v42, v41
	v_fmac_f32_e32 v32, 0xba800000, v40
	v_fmac_f32_e32 v34, 0xba800000, v40
	v_mul_f32_e32 v40, v35, v35
	v_mul_f32_e32 v42, v33, v33
	v_fmac_f32_e32 v40, v34, v34
	v_fmac_f32_e32 v42, v32, v32
	v_add_f32_e32 v40, v40, v42
	v_add_f32_e32 v40, v40, v41
	s_nop 0
	s_nop 1
	v_mov_b32_dpp v41, v40 quad_perm:[1,0,3,2] row_mask:0xf bank_mask:0xf
	v_add_f32_e32 v40, v40, v41
	s_nop 0
	s_nop 1
	v_mov_b32_dpp v41, v40 quad_perm:[2,3,0,1] row_mask:0xf bank_mask:0xf
	v_add_f32_e32 v40, v40, v41
	s_nop 0
	s_nop 1
	v_mov_b32_dpp v41, v40 row_shl:4 row_mask:0xf bank_mask:0x5
	v_mov_b32_dpp v41, v40 row_shr:4 row_mask:0xf bank_mask:0xa
	v_add_f32_e32 v40, v40, v41
	s_nop 0
	s_nop 1
	v_mov_b32_dpp v41, v40 row_ror:8 row_mask:0xf bank_mask:0xf
	v_add_f32_e32 v40, v40, v41
	s_nop 0
	v_mov_b32_e32 v41, v40
	v_mov_b32_e32 v200, v40
	s_nop 1
	v_permlane16_swap_b32_e32 v41, v200
	v_cndmask_b32_e64 v41, v200, v41, s[98:99]
	v_add_f32_e32 v40, v40, v41
	s_nop 0
	v_mov_b32_e32 v41, v40
	v_mov_b32_e32 v200, v40
	s_nop 1
	v_permlane32_swap_b32_e32 v41, v200
	v_cndmask_b32_e64 v41, v200, v41, s[100:101]
	s_cbranch_vccnz .LBB0_2245
	v_add_f32_e32 v40, v40, v41
	v_fmamk_f32 v40, v40, 0x3a800000, v126
	v_mul_f32_e32 v41, 0x4f800000, v40
	v_cmp_gt_f32_e32 vcc, s33, v40
	s_nop 1
	v_cndmask_b32_e32 v40, v40, v41, vcc
	v_sqrt_f32_e32 v41, v40
	s_nop 0
	v_add_u32_e32 v42, -1, v41
	v_fma_f32 v44, -v42, v41, v40
	v_add_u32_e32 v43, 1, v41
	v_cmp_ge_f32_e64 s[0:1], 0, v44
	s_nop 1
	v_cndmask_b32_e64 v42, v41, v42, s[0:1]
	v_fma_f32 v41, -v43, v41, v40
	v_cmp_lt_f32_e64 s[0:1], 0, v41
	s_nop 1
	v_cndmask_b32_e64 v41, v42, v43, s[0:1]
	v_mul_f32_e32 v42, 0x37800000, v41
	v_cndmask_b32_e32 v41, v41, v42, vcc
	v_cmp_class_f32_e32 vcc, v40, v127
	s_nop 1
	v_cndmask_b32_e32 v42, v41, v40, vcc
	v_div_scale_f32 v43, s[0:1], v42, v42, 1.0
	v_rcp_f32_e32 v44, v43
	v_lshl_add_u64 v[40:41], s[12:13], 0, v[112:113]
	v_fma_f32 v45, -v43, v44, 1.0
	v_fmac_f32_e32 v44, v45, v44
	v_div_scale_f32 v45, vcc, 1.0, v42, 1.0
	v_mul_f32_e32 v46, v45, v44
	v_fma_f32 v47, -v43, v46, v45
	v_fmac_f32_e32 v46, v47, v44
	v_fma_f32 v43, -v43, v46, v45
	v_div_fmas_f32 v43, v43, v44, v46
	v_div_fixup_f32 v42, v43, v42, 1.0
	v_pk_mul_f32 v[44:45], v[38:39], v[42:43] op_sel_hi:[1,0]
	v_pk_mul_f32 v[36:37], v[36:37], v[42:43] op_sel_hi:[1,0]
	v_pk_mul_f32 v[32:33], v[32:33], v[42:43] op_sel_hi:[1,0]
	v_pk_fma_f32 v[38:39], v[2:3], v[36:37], v[6:7]
	v_pk_fma_f32 v[36:37], v[0:1], v[44:45], v[4:5]
	global_store_dwordx4 v[40:41], v[36:39], off
	s_nop 1
	v_pk_mul_f32 v[36:37], v[54:55], v[42:43] op_sel_hi:[1,0]
	v_pk_mul_f32 v[38:39], v[52:53], v[42:43] op_sel_hi:[1,0]
	v_pk_fma_f32 v[36:37], v[8:9], v[36:37], v[16:17]
	v_pk_fma_f32 v[38:39], v[10:11], v[38:39], v[18:19]
	global_store_dwordx4 v[40:41], v[36:39], off offset:1024
	s_nop 1
	v_pk_mul_f32 v[36:37], v[74:75], v[42:43] op_sel_hi:[1,0]
	v_pk_mul_f32 v[38:39], v[72:73], v[42:43] op_sel_hi:[1,0]
	v_pk_fma_f32 v[36:37], v[12:13], v[36:37], v[20:21]
	v_pk_fma_f32 v[38:39], v[14:15], v[38:39], v[22:23]
	global_store_dwordx4 v[40:41], v[36:39], off offset:2048
	s_nop 1
	v_pk_mul_f32 v[36:37], v[34:35], v[42:43] op_sel_hi:[1,0]
	v_pk_fma_f32 v[34:35], v[26:27], v[32:33], v[30:31]
	v_pk_fma_f32 v[32:33], v[24:25], v[36:37], v[28:29]
	global_store_dwordx4 v[40:41], v[32:35], off offset:3072
	s_branch .LBB0_2245
